# P7 residual epilogue: all 16 residual loads issued up front, counted vmcnt
# speedup vs baseline: 1.0062x; 1.0062x over previous
; #define PG8_STAGE(bufoff, gbase, voff) do { _Pragma("unroll") for (int _i = 0; _i < 2; ++_i) \
;         __builtin_amdgcn_global_load_lds((const unsigned*)((const char*)(gbase) + (voff)[_i]), (PG8_LAS unsigned*)(lds + (bufoff) + ldsw + _i * 8192), 16, 0, 0); } while (0)
; #define PG8_LDA(dst, b, h) do { _Pragma("unroll") for (int m = 0; m < 4; ++m) _Pragma("unroll") for (int k = 0; k < 2; ++k) dst[m][k] = *(const PG8_LAS bf16x8*)(lds + PG8_SA(b, h) + aoff + m * 2048 + k * 1024); } while (0)
; #define PG8_LDB(dst, b, h) do { _Pragma("unroll") for (int n = 0; n < 2; ++n) _Pragma("unroll") for (int k = 0; k < 2; ++k) dst[n][k] = *(const PG8_LAS bf16x8*)(lds + PG8_SB(b, h) + boff + n * 2048 + k * 1024); } while (0)
; #define PG8_MMA(ai, bj, At, Bt) do { __builtin_amdgcn_s_setprio(1); _Pragma("unroll") for (int m = 0; m < 4; ++m) _Pragma("unroll") for (int n = 0; n < 2; ++n) _Pragma("unroll") for (int k = 0; k < 2; ++k) \
;         acc[ai][bj][m][n] = __builtin_amdgcn_mfma_f32_16x16x32_bf16(Bt[n][k], At[m][k], acc[ai][bj][m][n], 0, 0, 0); __builtin_amdgcn_s_setprio(0); } while (0)
; #define PG8_WAIT_V(n) asm volatile("s_waitcnt vmcnt(" #n ")" ::: "memory")
; #define PG8_BAR __builtin_amdgcn_s_barrier()
; template <class Epi, class Sched, bool ALIGN_EPI = false, bool SP2 = false>
; __device__ __forceinline__ void gemm_phase(PG8_LAS unsigned char* lds, const Gemm g, const Sched& S, const Epi& E) {
;     ...
;         for (int t = 0; t < nt; t += 2) {
;             const bool last = (t == nt - 2);
;             const char* a1 = cA + (size_t)(t + 1) * kstep;
;             const char* a2 = last ? nA : cA + (size_t)(t + 2) * kstep; const char* b2 = last ? nB : cB + (size_t)(t + 2) * kstep;
;             const char* a3 = a2 + kstep; const char* b3 = b2 + kstep;
;             if (last && has_next) S.a_ready(nxt);
;             if constexpr (SP2) {
;             PG8_LDB(B0, 0, 0); PG8_LDB(B1, 0, 1); PG8_SCHED; PG8_LDA(At, 0, 0); PG8_STAGE(PG8_SA(1, 1), a1 + hstep, voffA);
;             PG8_WAIT_V(8); PG8_WAIT_L(0); PG8_BAR; PG8_MMA(0, 0, At, B0); PG8_MMA(0, 1, At, B1); PG8_BAR; PG8_SCHED;
;             PG8_LDA(At, 0, 1); PG8_STAGE(PG8_SB(0, 0), b2, voffB); PG8_STAGE(PG8_SB(0, 1), b2 + hstep, voffB); PG8_STAGE(PG8_SA(0, 0), a2, voffA);
;             PG8_WAIT_V(8); PG8_WAIT_L(0); PG8_BAR; PG8_MMA(1, 0, At, B0); PG8_MMA(1, 1, At, B1); PG8_BAR; PG8_SCHED;
.LBB0_1198:
	s_add_u32 s6, s18, 0x100
	s_addc_u32 s7, s19, 0
	s_add_i32 s44, 0, 0x10000
	s_cmp_eq_u32 s42, s43
	s_cselect_b32 s23, s13, s7
	s_cselect_b32 s22, s12, s6
	v_add_u32_e32 v150, s44, v154
	s_cselect_b32 s21, s15, s17
	s_cselect_b32 s20, s14, s11
	s_add_i32 s45, 0, 0x14000
	ds_read_b128 v[128:131], v150
	ds_read_b128 v[142:145], v150 offset:1024
	ds_read_b128 v[146:149], v150 offset:2048
	ds_read_b128 v[158:161], v150 offset:3072
	v_add_u32_e32 v150, s45, v154
	ds_read_b128 v[162:165], v150
	ds_read_b128 v[166:169], v150 offset:1024
	ds_read_b128 v[170:173], v150 offset:2048
	ds_read_b128 v[174:177], v150 offset:3072
	v_lshl_add_u64 v[150:151], s[18:19], 0, v[138:139]
	s_add_i32 m0, s29, 0xc000
	ds_read_b128 v[178:181], v156
	ds_read_b128 v[182:185], v156 offset:1024
	ds_read_b128 v[194:197], v156 offset:2048
	ds_read_b128 v[198:201], v156 offset:3072
	ds_read_b128 v[202:205], v156 offset:4096
	ds_read_b128 v[210:213], v156 offset:5120
	ds_read_b128 v[214:217], v156 offset:6144
	ds_read_b128 v[218:221], v156 offset:7168
	global_load_lds_dwordx4 v[150:151], off
	v_lshl_add_u64 v[150:151], s[18:19], 0, v[140:141]
	s_add_i32 m0, s29, 0xe000
	s_nop 0
	global_load_lds_dwordx4 v[150:151], off
	s_waitcnt vmcnt(8)
	s_waitcnt lgkmcnt(0)
	s_barrier
	s_setprio 1
	s_waitcnt lgkmcnt(0)
	v_mfma_f32_16x16x32_bf16 v[124:127], v[128:131], v[178:181], v[124:127]
	v_mfma_f32_16x16x32_bf16 v[120:123], v[146:149], v[178:181], v[120:123]
	v_mfma_f32_16x16x32_bf16 v[108:111], v[128:131], v[194:197], v[108:111]
	v_mfma_f32_16x16x32_bf16 v[104:107], v[146:149], v[194:197], v[104:107]
	v_mfma_f32_16x16x32_bf16 v[92:95], v[128:131], v[202:205], v[92:95]
	v_mfma_f32_16x16x32_bf16 v[88:91], v[146:149], v[202:205], v[88:91]
	v_mfma_f32_16x16x32_bf16 v[76:79], v[128:131], v[214:217], v[76:79]
	v_mfma_f32_16x16x32_bf16 v[72:75], v[146:149], v[214:217], v[72:75]
	v_mfma_f32_16x16x32_bf16 v[124:127], v[142:145], v[182:185], v[124:127]
	v_mfma_f32_16x16x32_bf16 v[120:123], v[158:161], v[182:185], v[120:123]
	v_mfma_f32_16x16x32_bf16 v[108:111], v[142:145], v[198:201], v[108:111]
	v_mfma_f32_16x16x32_bf16 v[104:107], v[158:161], v[198:201], v[104:107]
	v_mfma_f32_16x16x32_bf16 v[92:95], v[142:145], v[210:213], v[92:95]
	v_mfma_f32_16x16x32_bf16 v[88:91], v[158:161], v[210:213], v[88:91]
	v_mfma_f32_16x16x32_bf16 v[76:79], v[142:145], v[218:221], v[76:79]
	v_mfma_f32_16x16x32_bf16 v[72:75], v[158:161], v[218:221], v[72:75]
	s_setprio 0
	s_setprio 1
	v_mfma_f32_16x16x32_bf16 v[116:119], v[162:165], v[178:181], v[116:119]
	v_mfma_f32_16x16x32_bf16 v[112:115], v[170:173], v[178:181], v[112:115]
	v_mfma_f32_16x16x32_bf16 v[100:103], v[162:165], v[194:197], v[100:103]
	v_mfma_f32_16x16x32_bf16 v[96:99], v[170:173], v[194:197], v[96:99]
	v_mfma_f32_16x16x32_bf16 v[84:87], v[162:165], v[202:205], v[84:87]
	v_mfma_f32_16x16x32_bf16 v[80:83], v[170:173], v[202:205], v[80:83]
	v_mfma_f32_16x16x32_bf16 v[68:71], v[162:165], v[214:217], v[68:71]
	v_mfma_f32_16x16x32_bf16 v[64:67], v[170:173], v[214:217], v[64:67]
	v_mfma_f32_16x16x32_bf16 v[116:119], v[166:169], v[182:185], v[116:119]
	v_mfma_f32_16x16x32_bf16 v[112:115], v[174:177], v[182:185], v[112:115]
	v_mfma_f32_16x16x32_bf16 v[100:103], v[166:169], v[198:201], v[100:103]
	v_mfma_f32_16x16x32_bf16 v[96:99], v[174:177], v[198:201], v[96:99]
	v_mfma_f32_16x16x32_bf16 v[84:87], v[166:169], v[210:213], v[84:87]
	v_mfma_f32_16x16x32_bf16 v[80:83], v[174:177], v[210:213], v[80:83]
	v_mfma_f32_16x16x32_bf16 v[68:71], v[166:169], v[218:221], v[68:71]
	v_mfma_f32_16x16x32_bf16 v[64:67], v[174:177], v[218:221], v[64:67]
	s_setprio 0
	s_barrier
	s_add_i32 s18, s44, s28
	v_lshl_add_u64 v[150:151], s[20:21], 0, v[188:189]
	s_mov_b32 m0, s18
	ds_read_b128 v[178:181], v156 offset:16384
	ds_read_b128 v[182:185], v156 offset:17408
	ds_read_b128 v[194:197], v156 offset:18432
	ds_read_b128 v[198:201], v156 offset:19456
	ds_read_b128 v[202:205], v156 offset:20480
	ds_read_b128 v[210:213], v156 offset:21504
	ds_read_b128 v[214:217], v156 offset:22528
	ds_read_b128 v[218:221], v156 offset:23552
	global_load_lds_dwordx4 v[150:151], off
	s_add_i32 m0, s18, 0x2000
	s_add_u32 s18, s20, 0xb0000
	v_lshl_add_u64 v[186:187], s[20:21], 0, v[136:137]
	s_addc_u32 s19, s21, 0
	s_add_i32 s44, s45, s28
	global_load_lds_dwordx4 v[186:187], off
	v_lshl_add_u64 v[190:191], s[18:19], 0, v[188:189]
	s_mov_b32 m0, s44
	v_lshl_add_u64 v[222:223], s[22:23], 0, v[134:135]
	global_load_lds_dwordx4 v[190:191], off
	v_lshl_add_u64 v[190:191], s[18:19], 0, v[136:137]
	s_add_i32 m0, s44, 0x2000
	s_nop 0
	global_load_lds_dwordx4 v[190:191], off
	v_lshl_add_u64 v[190:191], s[22:23], 0, v[132:133]
	s_mov_b32 m0, s29
	s_nop 0
	global_load_lds_dwordx4 v[190:191], off
	s_mov_b32 m0, s30
	s_nop 0
	global_load_lds_dwordx4 v[222:223], off
	s_waitcnt vmcnt(8)
	s_waitcnt lgkmcnt(0)
	s_barrier
; #define PG8_STAGE(bufoff, gbase, voff) do { _Pragma("unroll") for (int _i = 0; _i < 2; ++_i) \
;         __builtin_amdgcn_global_load_lds((const unsigned*)((const char*)(gbase) + (voff)[_i]), (PG8_LAS unsigned*)(lds + (bufoff) + ldsw + _i * 8192), 16, 0, 0); } while (0)
; #define PG8_LDA(dst, b, h) do { _Pragma("unroll") for (int m = 0; m < 4; ++m) _Pragma("unroll") for (int k = 0; k < 2; ++k) dst[m][k] = *(const PG8_LAS bf16x8*)(lds + PG8_SA(b, h) + aoff + m * 2048 + k * 1024); } while (0)
; #define PG8_LDB(dst, b, h) do { _Pragma("unroll") for (int n = 0; n < 2; ++n) _Pragma("unroll") for (int k = 0; k < 2; ++k) dst[n][k] = *(const PG8_LAS bf16x8*)(lds + PG8_SB(b, h) + boff + n * 2048 + k * 1024); } while (0)
; #define PG8_MMA(ai, bj, At, Bt) do { __builtin_amdgcn_s_setprio(1); _Pragma("unroll") for (int m = 0; m < 4; ++m) _Pragma("unroll") for (int n = 0; n < 2; ++n) _Pragma("unroll") for (int k = 0; k < 2; ++k) \
;         acc[ai][bj][m][n] = __builtin_amdgcn_mfma_f32_16x16x32_bf16(Bt[n][k], At[m][k], acc[ai][bj][m][n], 0, 0, 0); __builtin_amdgcn_s_setprio(0); } while (0)
; #define PG8_WAIT_V(n) asm volatile("s_waitcnt vmcnt(" #n ")" ::: "memory")
; #define PG8_WAIT_L(n) asm volatile("s_waitcnt lgkmcnt(" #n ")" ::: "memory")
; #define PG8_BAR __builtin_amdgcn_s_barrier()
; #define PG8_SCHED __builtin_amdgcn_sched_barrier(0)
; template <class Epi, class Sched, bool ALIGN_EPI = false, bool SP2 = false>
; __device__ __forceinline__ void gemm_phase(PG8_LAS unsigned char* lds, const Gemm g, const Sched& S, const Epi& E) {
;     ...
;             PG8_WAIT_V(8); PG8_WAIT_L(0); PG8_BAR; PG8_MMA(1, 0, At, B0); PG8_MMA(1, 1, At, B1); PG8_BAR; PG8_SCHED;
;             PG8_LDB(B0, 1, 0); PG8_LDB(B1, 1, 1); PG8_SCHED; PG8_LDA(At, 1, 0); PG8_STAGE(PG8_SA(0, 1), a2 + hstep, voffA);
;             PG8_WAIT_V(8); PG8_WAIT_L(0); PG8_BAR; PG8_MMA(0, 0, At, B0); PG8_MMA(0, 1, At, B1); PG8_BAR; PG8_SCHED;
;             PG8_LDA(At, 1, 1); PG8_STAGE(PG8_SB(1, 0), b3, voffB); PG8_STAGE(PG8_SB(1, 1), b3 + hstep, voffB); PG8_STAGE(PG8_SA(1, 0), a3, voffA);
;             PG8_WAIT_V(8); PG8_WAIT_L(0); PG8_BAR; PG8_MMA(1, 0, At, B0); PG8_MMA(1, 1, At, B1); PG8_BAR; PG8_SCHED;
	s_setprio 1
	s_waitcnt lgkmcnt(0)
	v_mfma_f32_16x16x32_bf16 v[60:63], v[128:131], v[178:181], v[60:63]
	v_mfma_f32_16x16x32_bf16 v[56:59], v[146:149], v[178:181], v[56:59]
	v_mfma_f32_16x16x32_bf16 v[44:47], v[128:131], v[194:197], v[44:47]
	v_mfma_f32_16x16x32_bf16 v[40:43], v[146:149], v[194:197], v[40:43]
	v_mfma_f32_16x16x32_bf16 v[28:31], v[128:131], v[202:205], v[28:31]
	v_mfma_f32_16x16x32_bf16 v[24:27], v[146:149], v[202:205], v[24:27]
	v_mfma_f32_16x16x32_bf16 v[12:15], v[128:131], v[214:217], v[12:15]
	v_mfma_f32_16x16x32_bf16 v[8:11], v[146:149], v[214:217], v[8:11]
	v_mfma_f32_16x16x32_bf16 v[60:63], v[142:145], v[182:185], v[60:63]
	v_mfma_f32_16x16x32_bf16 v[56:59], v[158:161], v[182:185], v[56:59]
	v_mfma_f32_16x16x32_bf16 v[44:47], v[142:145], v[198:201], v[44:47]
	v_mfma_f32_16x16x32_bf16 v[40:43], v[158:161], v[198:201], v[40:43]
	v_mfma_f32_16x16x32_bf16 v[28:31], v[142:145], v[210:213], v[28:31]
	v_mfma_f32_16x16x32_bf16 v[24:27], v[158:161], v[210:213], v[24:27]
	v_mfma_f32_16x16x32_bf16 v[12:15], v[142:145], v[218:221], v[12:15]
	v_mfma_f32_16x16x32_bf16 v[8:11], v[158:161], v[218:221], v[8:11]
	s_setprio 0
	s_setprio 1
	v_mfma_f32_16x16x32_bf16 v[52:55], v[162:165], v[178:181], v[52:55]
	v_mfma_f32_16x16x32_bf16 v[48:51], v[170:173], v[178:181], v[48:51]
	v_mfma_f32_16x16x32_bf16 v[36:39], v[162:165], v[194:197], v[36:39]
	v_mfma_f32_16x16x32_bf16 v[32:35], v[170:173], v[194:197], v[32:35]
	v_mfma_f32_16x16x32_bf16 v[20:23], v[162:165], v[202:205], v[20:23]
	v_mfma_f32_16x16x32_bf16 v[16:19], v[170:173], v[202:205], v[16:19]
	v_mfma_f32_16x16x32_bf16 v[4:7], v[162:165], v[214:217], v[4:7]
	v_mfma_f32_16x16x32_bf16 v[0:3], v[170:173], v[214:217], v[0:3]
	v_mfma_f32_16x16x32_bf16 v[52:55], v[166:169], v[182:185], v[52:55]
	v_mfma_f32_16x16x32_bf16 v[48:51], v[174:177], v[182:185], v[48:51]
	v_mfma_f32_16x16x32_bf16 v[36:39], v[166:169], v[198:201], v[36:39]
	v_mfma_f32_16x16x32_bf16 v[32:35], v[174:177], v[198:201], v[32:35]
	v_mfma_f32_16x16x32_bf16 v[20:23], v[166:169], v[210:213], v[20:23]
	v_mfma_f32_16x16x32_bf16 v[16:19], v[174:177], v[210:213], v[16:19]
	v_mfma_f32_16x16x32_bf16 v[4:7], v[166:169], v[218:221], v[4:7]
	v_mfma_f32_16x16x32_bf16 v[0:3], v[174:177], v[218:221], v[0:3]
	s_setprio 0
	s_barrier
	s_add_i32 s44, 0, 0x18000
	v_add_u32_e32 v157, s44, v154
	s_add_i32 s45, 0, 0x1c000
	ds_read_b128 v[128:131], v157
	ds_read_b128 v[142:145], v157 offset:1024
	ds_read_b128 v[146:149], v157 offset:2048
	ds_read_b128 v[158:161], v157 offset:3072
	v_add_u32_e32 v157, s45, v154
	ds_read_b128 v[162:165], v157
	ds_read_b128 v[166:169], v157 offset:1024
	ds_read_b128 v[170:173], v157 offset:2048
	ds_read_b128 v[174:177], v157 offset:3072
	s_add_u32 s18, s22, 0xb0000
	s_addc_u32 s19, s23, 0
	s_mov_b32 m0, s31
	v_lshl_add_u64 v[224:225], s[18:19], 0, v[132:133]
	ds_read_b128 v[178:181], v156 offset:32768
	ds_read_b128 v[182:185], v156 offset:33792
	ds_read_b128 v[194:197], v156 offset:34816
	ds_read_b128 v[198:201], v156 offset:35840
	ds_read_b128 v[202:205], v156 offset:36864
	ds_read_b128 v[210:213], v156 offset:37888
	ds_read_b128 v[214:217], v156 offset:38912
	ds_read_b128 v[218:221], v156 offset:39936
	global_load_lds_dwordx4 v[224:225], off
	v_lshl_add_u64 v[224:225], s[18:19], 0, v[134:135]
	s_mov_b32 m0, s33
	s_nop 0
	global_load_lds_dwordx4 v[224:225], off
	s_waitcnt vmcnt(8)
	s_waitcnt lgkmcnt(0)
	s_barrier
	s_setprio 1
	s_waitcnt lgkmcnt(0)
	v_mfma_f32_16x16x32_bf16 v[124:127], v[128:131], v[178:181], v[124:127]
	v_mfma_f32_16x16x32_bf16 v[120:123], v[146:149], v[178:181], v[120:123]
	v_mfma_f32_16x16x32_bf16 v[108:111], v[128:131], v[194:197], v[108:111]
	v_mfma_f32_16x16x32_bf16 v[104:107], v[146:149], v[194:197], v[104:107]
	v_mfma_f32_16x16x32_bf16 v[92:95], v[128:131], v[202:205], v[92:95]
	v_mfma_f32_16x16x32_bf16 v[88:91], v[146:149], v[202:205], v[88:91]
	v_mfma_f32_16x16x32_bf16 v[76:79], v[128:131], v[214:217], v[76:79]
	v_mfma_f32_16x16x32_bf16 v[72:75], v[146:149], v[214:217], v[72:75]
	v_mfma_f32_16x16x32_bf16 v[124:127], v[142:145], v[182:185], v[124:127]
	v_mfma_f32_16x16x32_bf16 v[120:123], v[158:161], v[182:185], v[120:123]
	v_mfma_f32_16x16x32_bf16 v[108:111], v[142:145], v[198:201], v[108:111]
	v_mfma_f32_16x16x32_bf16 v[104:107], v[158:161], v[198:201], v[104:107]
	v_mfma_f32_16x16x32_bf16 v[92:95], v[142:145], v[210:213], v[92:95]
	v_mfma_f32_16x16x32_bf16 v[88:91], v[158:161], v[210:213], v[88:91]
	v_mfma_f32_16x16x32_bf16 v[76:79], v[142:145], v[218:221], v[76:79]
	v_mfma_f32_16x16x32_bf16 v[72:75], v[158:161], v[218:221], v[72:75]
	s_setprio 0
	s_setprio 1
	v_mfma_f32_16x16x32_bf16 v[116:119], v[162:165], v[178:181], v[116:119]
	v_mfma_f32_16x16x32_bf16 v[112:115], v[170:173], v[178:181], v[112:115]
	v_mfma_f32_16x16x32_bf16 v[100:103], v[162:165], v[194:197], v[100:103]
	v_mfma_f32_16x16x32_bf16 v[96:99], v[170:173], v[194:197], v[96:99]
	v_mfma_f32_16x16x32_bf16 v[84:87], v[162:165], v[202:205], v[84:87]
	v_mfma_f32_16x16x32_bf16 v[80:83], v[170:173], v[202:205], v[80:83]
	v_mfma_f32_16x16x32_bf16 v[68:71], v[162:165], v[214:217], v[68:71]
	v_mfma_f32_16x16x32_bf16 v[64:67], v[170:173], v[214:217], v[64:67]
	v_mfma_f32_16x16x32_bf16 v[116:119], v[166:169], v[182:185], v[116:119]
	v_mfma_f32_16x16x32_bf16 v[112:115], v[174:177], v[182:185], v[112:115]
	v_mfma_f32_16x16x32_bf16 v[100:103], v[166:169], v[198:201], v[100:103]
	v_mfma_f32_16x16x32_bf16 v[96:99], v[174:177], v[198:201], v[96:99]
	v_mfma_f32_16x16x32_bf16 v[84:87], v[166:169], v[210:213], v[84:87]
	v_mfma_f32_16x16x32_bf16 v[80:83], v[174:177], v[210:213], v[80:83]
	v_mfma_f32_16x16x32_bf16 v[68:71], v[166:169], v[218:221], v[68:71]
	v_mfma_f32_16x16x32_bf16 v[64:67], v[174:177], v[218:221], v[64:67]
	s_setprio 0
	s_barrier
; __device__ __forceinline__ u32x4 pack8(const f32x4 a, const f32x4 b) { u32x4 w; w.x = cvt_pk_bf16(a[0], a[1]); w.y = cvt_pk_bf16(a[2], a[3]); w.z = cvt_pk_bf16(b[0], b[1]); w.w = cvt_pk_bf16(b[2], b[3]); return w; }
; #define PG8_STAGE(bufoff, gbase, voff) do { _Pragma("unroll") for (int _i = 0; _i < 2; ++_i) \
;         __builtin_amdgcn_global_load_lds((const unsigned*)((const char*)(gbase) + (voff)[_i]), (PG8_LAS unsigned*)(lds + (bufoff) + ldsw + _i * 8192), 16, 0, 0); } while (0)
; #define PG8_LDA(dst, b, h) do { _Pragma("unroll") for (int m = 0; m < 4; ++m) _Pragma("unroll") for (int k = 0; k < 2; ++k) dst[m][k] = *(const PG8_LAS bf16x8*)(lds + PG8_SA(b, h) + aoff + m * 2048 + k * 1024); } while (0)
;     __device__ __forceinline__ void operator()(const f32x4 (&acc)[2][2][4][2], const Unit& u, int wr, int wc, int fr, int fq) const {
;         const int row0 = u.pm * BM + wr * 64 + fr; const int col0 = u.pn * BM + wc * 32 + 8 * fq;
;         const bool part = u.nkt != nkt_full;
;         bf16_t* pbase = PART + ((long)(u.kt0 / u.nkt) * prows - row0p) * 1024;
; #pragma unroll
;         for (int ai = 0; ai < 2; ++ai)
; #pragma unroll
;             for (int m = 0; m < 4; ++m) { const size_t ro = (size_t)(row0 + ai * HALF + m * 16) * 1024 + col0;
; #pragma unroll
;                 for (int bj = 0; bj < 2; ++bj) { const size_t o = ro + bj * HALF;
;                     if (part) *(u32x4*)(pbase + o) = pack8(acc[ai][bj][m][0], acc[ai][bj][m][1]);
;                     else { f32x4 r0, r1;
;                         if (X32) { r0 = *(const f32x4*)(X32 + o); r1 = *(const f32x4*)(X32 + o + 4); }
;                         else { const u32x4 hw = *(const u32x4*)(H + o); r0 = (f32x4){bflo(hw.x), bfhi(hw.x), bflo(hw.y), bfhi(hw.y)}; r1 = (f32x4){bflo(hw.z), bfhi(hw.z), bflo(hw.w), bfhi(hw.w)}; }
;                         *(u32x4*)(H + o) = pack8(r0 + acc[ai][bj][m][0], r1 + acc[ai][bj][m][1]); } }
; template <class Epi, class Sched, bool ALIGN_EPI = false, bool SP2 = false>
; __device__ __forceinline__ void gemm_phase(PG8_LAS unsigned char* lds, const Gemm g, const Sched& S, const Epi& E) {
;     ...
;             PG8_LDA(At, 1, 1); PG8_STAGE(PG8_SB(1, 0), b3, voffB); PG8_STAGE(PG8_SB(1, 1), b3 + hstep, voffB); PG8_STAGE(PG8_SA(1, 0), a3, voffA);
;             PG8_WAIT_V(8); PG8_WAIT_L(0); PG8_BAR; PG8_MMA(1, 0, At, B0); PG8_MMA(1, 1, At, B1); PG8_BAR; PG8_SCHED;
	s_add_i32 s18, s44, s28
	v_lshl_add_u64 v[150:151], v[150:151], 0, s[48:49]
	s_mov_b32 m0, s18
	ds_read_b128 v[178:181], v156 offset:49152
	ds_read_b128 v[182:185], v156 offset:50176
	ds_read_b128 v[194:197], v156 offset:51200
	ds_read_b128 v[198:201], v156 offset:52224
	ds_read_b128 v[202:205], v156 offset:53248
	ds_read_b128 v[210:213], v156 offset:54272
	ds_read_b128 v[214:217], v156 offset:55296
	ds_read_b128 v[218:221], v156 offset:56320
	global_load_lds_dwordx4 v[150:151], off
	s_add_i32 m0, s18, 0x2000
	s_add_u32 s18, s20, 0xb0080
	v_lshl_add_u64 v[150:151], v[186:187], 0, s[48:49]
	s_addc_u32 s19, s21, 0
	s_add_i32 s20, s45, s28
	global_load_lds_dwordx4 v[150:151], off
	v_lshl_add_u64 v[150:151], s[18:19], 0, v[188:189]
	s_mov_b32 m0, s20
	s_nop 0
	global_load_lds_dwordx4 v[150:151], off
	v_lshl_add_u64 v[150:151], s[18:19], 0, v[136:137]
	s_add_i32 m0, s20, 0x2000
	s_nop 0
	global_load_lds_dwordx4 v[150:151], off
	v_lshl_add_u64 v[150:151], v[190:191], 0, s[48:49]
	s_mov_b32 m0, s34
	s_nop 0
	global_load_lds_dwordx4 v[150:151], off
	v_lshl_add_u64 v[150:151], v[222:223], 0, s[48:49]
	s_mov_b32 m0, s35
	s_nop 0
	global_load_lds_dwordx4 v[150:151], off
	s_waitcnt vmcnt(8)
	s_waitcnt lgkmcnt(0)
	s_barrier
	s_setprio 1
	s_waitcnt lgkmcnt(0)
	v_mfma_f32_16x16x32_bf16 v[60:63], v[128:131], v[178:181], v[60:63]
	v_mfma_f32_16x16x32_bf16 v[56:59], v[146:149], v[178:181], v[56:59]
	v_mfma_f32_16x16x32_bf16 v[44:47], v[128:131], v[194:197], v[44:47]
	v_mfma_f32_16x16x32_bf16 v[40:43], v[146:149], v[194:197], v[40:43]
	v_mfma_f32_16x16x32_bf16 v[28:31], v[128:131], v[202:205], v[28:31]
	v_mfma_f32_16x16x32_bf16 v[24:27], v[146:149], v[202:205], v[24:27]
	v_mfma_f32_16x16x32_bf16 v[12:15], v[128:131], v[214:217], v[12:15]
	v_mfma_f32_16x16x32_bf16 v[8:11], v[146:149], v[214:217], v[8:11]
	v_mfma_f32_16x16x32_bf16 v[60:63], v[142:145], v[182:185], v[60:63]
	v_mfma_f32_16x16x32_bf16 v[56:59], v[158:161], v[182:185], v[56:59]
	v_mfma_f32_16x16x32_bf16 v[44:47], v[142:145], v[198:201], v[44:47]
	v_mfma_f32_16x16x32_bf16 v[40:43], v[158:161], v[198:201], v[40:43]
	v_mfma_f32_16x16x32_bf16 v[28:31], v[142:145], v[210:213], v[28:31]
	v_mfma_f32_16x16x32_bf16 v[24:27], v[158:161], v[210:213], v[24:27]
	v_mfma_f32_16x16x32_bf16 v[12:15], v[142:145], v[218:221], v[12:15]
	v_mfma_f32_16x16x32_bf16 v[8:11], v[158:161], v[218:221], v[8:11]
	s_setprio 0
	s_setprio 1
	v_mfma_f32_16x16x32_bf16 v[52:55], v[162:165], v[178:181], v[52:55]
	v_mfma_f32_16x16x32_bf16 v[48:51], v[170:173], v[178:181], v[48:51]
	v_mfma_f32_16x16x32_bf16 v[36:39], v[162:165], v[194:197], v[36:39]
	v_mfma_f32_16x16x32_bf16 v[32:35], v[170:173], v[194:197], v[32:35]
	v_mfma_f32_16x16x32_bf16 v[20:23], v[162:165], v[202:205], v[20:23]
	v_mfma_f32_16x16x32_bf16 v[16:19], v[170:173], v[202:205], v[16:19]
	v_mfma_f32_16x16x32_bf16 v[4:7], v[162:165], v[214:217], v[4:7]
	v_mfma_f32_16x16x32_bf16 v[0:3], v[170:173], v[214:217], v[0:3]
	v_mfma_f32_16x16x32_bf16 v[52:55], v[166:169], v[182:185], v[52:55]
	v_mfma_f32_16x16x32_bf16 v[48:51], v[174:177], v[182:185], v[48:51]
	v_mfma_f32_16x16x32_bf16 v[36:39], v[166:169], v[198:201], v[36:39]
	v_mfma_f32_16x16x32_bf16 v[32:35], v[174:177], v[198:201], v[32:35]
	v_mfma_f32_16x16x32_bf16 v[20:23], v[166:169], v[210:213], v[20:23]
	v_mfma_f32_16x16x32_bf16 v[16:19], v[174:177], v[210:213], v[16:19]
	v_mfma_f32_16x16x32_bf16 v[4:7], v[166:169], v[218:221], v[4:7]
	v_mfma_f32_16x16x32_bf16 v[0:3], v[174:177], v[218:221], v[0:3]
	s_setprio 0
	s_barrier
	s_add_i32 s20, s43, 2
	s_add_u32 s11, s11, 0x100
	s_addc_u32 s17, s17, 0
	s_cmp_ge_u32 s43, s42
	s_mov_b64 s[18:19], s[6:7]
	s_mov_b32 s43, s20
	s_cbranch_scc0 .LBB0_1198
	s_cmp_lg_u32 s42, 44
	s_cbranch_scc1 .Lp7_nopre
	v_readlane_b32 s16, v254, 17
	v_readlane_b32 s17, v254, 18
	v_lshl_add_u32 v150, s40, 8, v153
	v_lshl_or_b32 v151, s41, 8, v155
	v_lshlrev_b32_e32 v150, 11, v150
	v_lshl_add_u32 v150, v151, 1, v150
	s_mov_b64 s[6:7], s[16:17]
	global_load_dwordx4 v[128:131], v150, s[6:7]
	global_load_dwordx4 v[142:145], v150, s[6:7] offset:256
	s_add_u32 s6, s16, 0x8000
	s_addc_u32 s7, s17, 0
	global_load_dwordx4 v[146:149], v150, s[6:7]
	global_load_dwordx4 v[158:161], v150, s[6:7] offset:256
	s_add_u32 s6, s16, 0x10000
	s_addc_u32 s7, s17, 0
	global_load_dwordx4 v[162:165], v150, s[6:7]
	global_load_dwordx4 v[166:169], v150, s[6:7] offset:256
	s_add_u32 s6, s16, 0x18000
	s_addc_u32 s7, s17, 0
	global_load_dwordx4 v[170:173], v150, s[6:7]
	global_load_dwordx4 v[174:177], v150, s[6:7] offset:256
	s_add_u32 s6, s16, 0x40000
	s_addc_u32 s7, s17, 0
	global_load_dwordx4 v[178:181], v150, s[6:7]
	global_load_dwordx4 v[182:185], v150, s[6:7] offset:256
	s_add_u32 s6, s16, 0x48000
	s_addc_u32 s7, s17, 0
	global_load_dwordx4 v[194:197], v150, s[6:7]
	global_load_dwordx4 v[198:201], v150, s[6:7] offset:256
	s_add_u32 s6, s16, 0x50000
	s_addc_u32 s7, s17, 0
	global_load_dwordx4 v[202:205], v150, s[6:7]
	global_load_dwordx4 v[210:213], v150, s[6:7] offset:256
	s_add_u32 s6, s16, 0x58000
	s_addc_u32 s7, s17, 0
	global_load_dwordx4 v[214:217], v150, s[6:7]
	global_load_dwordx4 v[218:221], v150, s[6:7] offset:256
.Lp7_nopre:
	s_and_b64 vcc, exec, s[8:9]
	s_cbranch_vccz .LBB0_1201
	s_barrier
; __device__ __forceinline__ u32x4 pack8(const f32x4 a, const f32x4 b) { u32x4 w; w.x = cvt_pk_bf16(a[0], a[1]); w.y = cvt_pk_bf16(a[2], a[3]); w.z = cvt_pk_bf16(b[0], b[1]); w.w = cvt_pk_bf16(b[2], b[3]); return w; }
;     __device__ __forceinline__ void operator()(const f32x4 (&acc)[2][2][4][2], const Unit& u, int wr, int wc, int fr, int fq) const {
;         const int row0 = u.pm * BM + wr * 64 + fr; const int col0 = u.pn * BM + wc * 32 + 8 * fq;
;         const bool part = u.nkt != nkt_full;
;         bf16_t* pbase = PART + ((long)(u.kt0 / u.nkt) * prows - row0p) * 1024;
; #pragma unroll
;         for (int ai = 0; ai < 2; ++ai)
; #pragma unroll
;             for (int m = 0; m < 4; ++m) { const size_t ro = (size_t)(row0 + ai * HALF + m * 16) * 1024 + col0;
; #pragma unroll
;                 for (int bj = 0; bj < 2; ++bj) { const size_t o = ro + bj * HALF;
;                     if (part) *(u32x4*)(pbase + o) = pack8(acc[ai][bj][m][0], acc[ai][bj][m][1]);
;                     else { f32x4 r0, r1;
;                         if (X32) { r0 = *(const f32x4*)(X32 + o); r1 = *(const f32x4*)(X32 + o + 4); }
;                         else { const u32x4 hw = *(const u32x4*)(H + o); r0 = (f32x4){bflo(hw.x), bfhi(hw.x), bflo(hw.y), bfhi(hw.y)}; r1 = (f32x4){bflo(hw.z), bfhi(hw.z), bflo(hw.w), bfhi(hw.w)}; }
;                         *(u32x4*)(H + o) = pack8(r0 + acc[ai][bj][m][0], r1 + acc[ai][bj][m][1]); } }
;                 asm volatile("" ::: "memory"); }
.LBB0_1201:
	s_cmp_lg_u32 s42, 44
	s_cbranch_scc1 .Lp7_slow
	s_mov_b64 s[6:7], s[16:17]
	s_waitcnt vmcnt(15)
	v_lshlrev_b32_e32 v151, 16, v128
	v_and_b32_e32 v128, 0xffff0000, v128
	v_add_f32_e32 v124, v124, v151
	v_add_f32_e32 v125, v125, v128
	v_lshlrev_b32_e32 v151, 16, v129
	v_and_b32_e32 v129, 0xffff0000, v129
	v_add_f32_e32 v126, v126, v151
	v_add_f32_e32 v127, v127, v129
	v_lshlrev_b32_e32 v151, 16, v130
	v_and_b32_e32 v130, 0xffff0000, v130
	v_add_f32_e32 v120, v120, v151
	v_add_f32_e32 v121, v121, v130
	v_lshlrev_b32_e32 v151, 16, v131
	v_and_b32_e32 v131, 0xffff0000, v131
	v_add_f32_e32 v122, v122, v151
	v_add_f32_e32 v123, v123, v131
	v_cvt_pk_bf16_f32 v128, v124, v125
	v_cvt_pk_bf16_f32 v129, v126, v127
	v_cvt_pk_bf16_f32 v130, v120, v121
	v_cvt_pk_bf16_f32 v131, v122, v123
	global_store_dwordx4 v150, v[128:131], s[6:7]
	s_waitcnt vmcnt(15)
	v_lshlrev_b32_e32 v151, 16, v142
	v_and_b32_e32 v142, 0xffff0000, v142
	v_add_f32_e32 v116, v116, v151
	v_add_f32_e32 v117, v117, v142
	v_lshlrev_b32_e32 v151, 16, v143
	v_and_b32_e32 v143, 0xffff0000, v143
	v_add_f32_e32 v118, v118, v151
	v_add_f32_e32 v119, v119, v143
	v_lshlrev_b32_e32 v151, 16, v144
	v_and_b32_e32 v144, 0xffff0000, v144
	v_add_f32_e32 v112, v112, v151
	v_add_f32_e32 v113, v113, v144
	v_lshlrev_b32_e32 v151, 16, v145
	v_and_b32_e32 v145, 0xffff0000, v145
	v_add_f32_e32 v114, v114, v151
	v_add_f32_e32 v115, v115, v145
	v_cvt_pk_bf16_f32 v142, v116, v117
	v_cvt_pk_bf16_f32 v143, v118, v119
	v_cvt_pk_bf16_f32 v144, v112, v113
	v_cvt_pk_bf16_f32 v145, v114, v115
	global_store_dwordx4 v150, v[142:145], s[6:7] offset:256
	s_add_u32 s6, s16, 0x8000
	s_addc_u32 s7, s17, 0
	s_waitcnt vmcnt(15)
	v_lshlrev_b32_e32 v151, 16, v146
	v_and_b32_e32 v146, 0xffff0000, v146
	v_add_f32_e32 v108, v108, v151
	v_add_f32_e32 v109, v109, v146
	v_lshlrev_b32_e32 v151, 16, v147
	v_and_b32_e32 v147, 0xffff0000, v147
	v_add_f32_e32 v110, v110, v151
	v_add_f32_e32 v111, v111, v147
	v_lshlrev_b32_e32 v151, 16, v148
	v_and_b32_e32 v148, 0xffff0000, v148
	v_add_f32_e32 v104, v104, v151
	v_add_f32_e32 v105, v105, v148
	v_lshlrev_b32_e32 v151, 16, v149
	v_and_b32_e32 v149, 0xffff0000, v149
	v_add_f32_e32 v106, v106, v151
	v_add_f32_e32 v107, v107, v149
	v_cvt_pk_bf16_f32 v146, v108, v109
	v_cvt_pk_bf16_f32 v147, v110, v111
	v_cvt_pk_bf16_f32 v148, v104, v105
	v_cvt_pk_bf16_f32 v149, v106, v107
	global_store_dwordx4 v150, v[146:149], s[6:7]
	s_waitcnt vmcnt(15)
	v_lshlrev_b32_e32 v151, 16, v158
	v_and_b32_e32 v158, 0xffff0000, v158
	v_add_f32_e32 v100, v100, v151
	v_add_f32_e32 v101, v101, v158
	v_lshlrev_b32_e32 v151, 16, v159
	v_and_b32_e32 v159, 0xffff0000, v159
	v_add_f32_e32 v102, v102, v151
	v_add_f32_e32 v103, v103, v159
	v_lshlrev_b32_e32 v151, 16, v160
	v_and_b32_e32 v160, 0xffff0000, v160
	v_add_f32_e32 v96, v96, v151
	v_add_f32_e32 v97, v97, v160
	v_lshlrev_b32_e32 v151, 16, v161
	v_and_b32_e32 v161, 0xffff0000, v161
	v_add_f32_e32 v98, v98, v151
	v_add_f32_e32 v99, v99, v161
	v_cvt_pk_bf16_f32 v158, v100, v101
	v_cvt_pk_bf16_f32 v159, v102, v103
	v_cvt_pk_bf16_f32 v160, v96, v97
	v_cvt_pk_bf16_f32 v161, v98, v99
	global_store_dwordx4 v150, v[158:161], s[6:7] offset:256
	s_add_u32 s6, s16, 0x10000
	s_addc_u32 s7, s17, 0
	s_waitcnt vmcnt(15)
	v_lshlrev_b32_e32 v151, 16, v162
	v_and_b32_e32 v162, 0xffff0000, v162
	v_add_f32_e32 v92, v92, v151
	v_add_f32_e32 v93, v93, v162
	v_lshlrev_b32_e32 v151, 16, v163
	v_and_b32_e32 v163, 0xffff0000, v163
	v_add_f32_e32 v94, v94, v151
	v_add_f32_e32 v95, v95, v163
	v_lshlrev_b32_e32 v151, 16, v164
	v_and_b32_e32 v164, 0xffff0000, v164
	v_add_f32_e32 v88, v88, v151
	v_add_f32_e32 v89, v89, v164
	v_lshlrev_b32_e32 v151, 16, v165
	v_and_b32_e32 v165, 0xffff0000, v165
	v_add_f32_e32 v90, v90, v151
	v_add_f32_e32 v91, v91, v165
	v_cvt_pk_bf16_f32 v162, v92, v93
	v_cvt_pk_bf16_f32 v163, v94, v95
	v_cvt_pk_bf16_f32 v164, v88, v89
	v_cvt_pk_bf16_f32 v165, v90, v91
	global_store_dwordx4 v150, v[162:165], s[6:7]
	s_waitcnt vmcnt(15)
	v_lshlrev_b32_e32 v151, 16, v166
	v_and_b32_e32 v166, 0xffff0000, v166
	v_add_f32_e32 v84, v84, v151
	v_add_f32_e32 v85, v85, v166
	v_lshlrev_b32_e32 v151, 16, v167
	v_and_b32_e32 v167, 0xffff0000, v167
	v_add_f32_e32 v86, v86, v151
	v_add_f32_e32 v87, v87, v167
	v_lshlrev_b32_e32 v151, 16, v168
	v_and_b32_e32 v168, 0xffff0000, v168
	v_add_f32_e32 v80, v80, v151
	v_add_f32_e32 v81, v81, v168
	v_lshlrev_b32_e32 v151, 16, v169
	v_and_b32_e32 v169, 0xffff0000, v169
	v_add_f32_e32 v82, v82, v151
	v_add_f32_e32 v83, v83, v169
	v_cvt_pk_bf16_f32 v166, v84, v85
	v_cvt_pk_bf16_f32 v167, v86, v87
	v_cvt_pk_bf16_f32 v168, v80, v81
	v_cvt_pk_bf16_f32 v169, v82, v83
	global_store_dwordx4 v150, v[166:169], s[6:7] offset:256
	s_add_u32 s6, s16, 0x18000
	s_addc_u32 s7, s17, 0
	s_waitcnt vmcnt(15)
	v_lshlrev_b32_e32 v151, 16, v170
	v_and_b32_e32 v170, 0xffff0000, v170
	v_add_f32_e32 v76, v76, v151
	v_add_f32_e32 v77, v77, v170
	v_lshlrev_b32_e32 v151, 16, v171
	v_and_b32_e32 v171, 0xffff0000, v171
	v_add_f32_e32 v78, v78, v151
	v_add_f32_e32 v79, v79, v171
	v_lshlrev_b32_e32 v151, 16, v172
	v_and_b32_e32 v172, 0xffff0000, v172
	v_add_f32_e32 v72, v72, v151
	v_add_f32_e32 v73, v73, v172
	v_lshlrev_b32_e32 v151, 16, v173
	v_and_b32_e32 v173, 0xffff0000, v173
	v_add_f32_e32 v74, v74, v151
	v_add_f32_e32 v75, v75, v173
	v_cvt_pk_bf16_f32 v170, v76, v77
	v_cvt_pk_bf16_f32 v171, v78, v79
	v_cvt_pk_bf16_f32 v172, v72, v73
	v_cvt_pk_bf16_f32 v173, v74, v75
	global_store_dwordx4 v150, v[170:173], s[6:7]
	s_waitcnt vmcnt(15)
; __device__ __forceinline__ u32x4 pack8(const f32x4 a, const f32x4 b) { u32x4 w; w.x = cvt_pk_bf16(a[0], a[1]); w.y = cvt_pk_bf16(a[2], a[3]); w.z = cvt_pk_bf16(b[0], b[1]); w.w = cvt_pk_bf16(b[2], b[3]); return w; }
;     __device__ __forceinline__ void operator()(const f32x4 (&acc)[2][2][4][2], const Unit& u, int wr, int wc, int fr, int fq) const {
;     ...
;             for (int m = 0; m < 4; ++m) { const size_t ro = (size_t)(row0 + ai * HALF + m * 16) * 1024 + col0;
; #pragma unroll
;                 for (int bj = 0; bj < 2; ++bj) { const size_t o = ro + bj * HALF;
;                     if (part) *(u32x4*)(pbase + o) = pack8(acc[ai][bj][m][0], acc[ai][bj][m][1]);
;                     else { f32x4 r0, r1;
;                         if (X32) { r0 = *(const f32x4*)(X32 + o); r1 = *(const f32x4*)(X32 + o + 4); }
;                         else { const u32x4 hw = *(const u32x4*)(H + o); r0 = (f32x4){bflo(hw.x), bfhi(hw.x), bflo(hw.y), bfhi(hw.y)}; r1 = (f32x4){bflo(hw.z), bfhi(hw.z), bflo(hw.w), bfhi(hw.w)}; }
;                         *(u32x4*)(H + o) = pack8(r0 + acc[ai][bj][m][0], r1 + acc[ai][bj][m][1]); } }
;                 asm volatile("" ::: "memory"); }
	v_lshlrev_b32_e32 v151, 16, v174
	v_and_b32_e32 v174, 0xffff0000, v174
	v_add_f32_e32 v68, v68, v151
	v_add_f32_e32 v69, v69, v174
	v_lshlrev_b32_e32 v151, 16, v175
	v_and_b32_e32 v175, 0xffff0000, v175
	v_add_f32_e32 v70, v70, v151
	v_add_f32_e32 v71, v71, v175
	v_lshlrev_b32_e32 v151, 16, v176
	v_and_b32_e32 v176, 0xffff0000, v176
	v_add_f32_e32 v64, v64, v151
	v_add_f32_e32 v65, v65, v176
	v_lshlrev_b32_e32 v151, 16, v177
	v_and_b32_e32 v177, 0xffff0000, v177
	v_add_f32_e32 v66, v66, v151
	v_add_f32_e32 v67, v67, v177
	v_cvt_pk_bf16_f32 v174, v68, v69
	v_cvt_pk_bf16_f32 v175, v70, v71
	v_cvt_pk_bf16_f32 v176, v64, v65
	v_cvt_pk_bf16_f32 v177, v66, v67
	global_store_dwordx4 v150, v[174:177], s[6:7] offset:256
	s_add_u32 s6, s16, 0x40000
	s_addc_u32 s7, s17, 0
	s_waitcnt vmcnt(15)
	v_lshlrev_b32_e32 v151, 16, v178
	v_and_b32_e32 v178, 0xffff0000, v178
	v_add_f32_e32 v60, v60, v151
	v_add_f32_e32 v61, v61, v178
	v_lshlrev_b32_e32 v151, 16, v179
	v_and_b32_e32 v179, 0xffff0000, v179
	v_add_f32_e32 v62, v62, v151
	v_add_f32_e32 v63, v63, v179
	v_lshlrev_b32_e32 v151, 16, v180
	v_and_b32_e32 v180, 0xffff0000, v180
	v_add_f32_e32 v56, v56, v151
	v_add_f32_e32 v57, v57, v180
	v_lshlrev_b32_e32 v151, 16, v181
	v_and_b32_e32 v181, 0xffff0000, v181
	v_add_f32_e32 v58, v58, v151
	v_add_f32_e32 v59, v59, v181
	v_cvt_pk_bf16_f32 v178, v60, v61
	v_cvt_pk_bf16_f32 v179, v62, v63
	v_cvt_pk_bf16_f32 v180, v56, v57
	v_cvt_pk_bf16_f32 v181, v58, v59
	global_store_dwordx4 v150, v[178:181], s[6:7]
	s_waitcnt vmcnt(15)
	v_lshlrev_b32_e32 v151, 16, v182
	v_and_b32_e32 v182, 0xffff0000, v182
	v_add_f32_e32 v52, v52, v151
	v_add_f32_e32 v53, v53, v182
	v_lshlrev_b32_e32 v151, 16, v183
	v_and_b32_e32 v183, 0xffff0000, v183
	v_add_f32_e32 v54, v54, v151
	v_add_f32_e32 v55, v55, v183
	v_lshlrev_b32_e32 v151, 16, v184
	v_and_b32_e32 v184, 0xffff0000, v184
	v_add_f32_e32 v48, v48, v151
	v_add_f32_e32 v49, v49, v184
	v_lshlrev_b32_e32 v151, 16, v185
	v_and_b32_e32 v185, 0xffff0000, v185
	v_add_f32_e32 v50, v50, v151
	v_add_f32_e32 v51, v51, v185
	v_cvt_pk_bf16_f32 v182, v52, v53
	v_cvt_pk_bf16_f32 v183, v54, v55
	v_cvt_pk_bf16_f32 v184, v48, v49
	v_cvt_pk_bf16_f32 v185, v50, v51
	global_store_dwordx4 v150, v[182:185], s[6:7] offset:256
	s_add_u32 s6, s16, 0x48000
	s_addc_u32 s7, s17, 0
	s_waitcnt vmcnt(15)
	v_lshlrev_b32_e32 v151, 16, v194
	v_and_b32_e32 v194, 0xffff0000, v194
	v_add_f32_e32 v44, v44, v151
	v_add_f32_e32 v45, v45, v194
	v_lshlrev_b32_e32 v151, 16, v195
	v_and_b32_e32 v195, 0xffff0000, v195
	v_add_f32_e32 v46, v46, v151
	v_add_f32_e32 v47, v47, v195
	v_lshlrev_b32_e32 v151, 16, v196
	v_and_b32_e32 v196, 0xffff0000, v196
	v_add_f32_e32 v40, v40, v151
	v_add_f32_e32 v41, v41, v196
	v_lshlrev_b32_e32 v151, 16, v197
	v_and_b32_e32 v197, 0xffff0000, v197
	v_add_f32_e32 v42, v42, v151
	v_add_f32_e32 v43, v43, v197
	v_cvt_pk_bf16_f32 v194, v44, v45
	v_cvt_pk_bf16_f32 v195, v46, v47
	v_cvt_pk_bf16_f32 v196, v40, v41
	v_cvt_pk_bf16_f32 v197, v42, v43
	global_store_dwordx4 v150, v[194:197], s[6:7]
	s_waitcnt vmcnt(15)
	v_lshlrev_b32_e32 v151, 16, v198
	v_and_b32_e32 v198, 0xffff0000, v198
	v_add_f32_e32 v36, v36, v151
	v_add_f32_e32 v37, v37, v198
	v_lshlrev_b32_e32 v151, 16, v199
	v_and_b32_e32 v199, 0xffff0000, v199
	v_add_f32_e32 v38, v38, v151
	v_add_f32_e32 v39, v39, v199
	v_lshlrev_b32_e32 v151, 16, v200
	v_and_b32_e32 v200, 0xffff0000, v200
	v_add_f32_e32 v32, v32, v151
	v_add_f32_e32 v33, v33, v200
	v_lshlrev_b32_e32 v151, 16, v201
	v_and_b32_e32 v201, 0xffff0000, v201
	v_add_f32_e32 v34, v34, v151
	v_add_f32_e32 v35, v35, v201
	v_cvt_pk_bf16_f32 v198, v36, v37
	v_cvt_pk_bf16_f32 v199, v38, v39
	v_cvt_pk_bf16_f32 v200, v32, v33
	v_cvt_pk_bf16_f32 v201, v34, v35
	global_store_dwordx4 v150, v[198:201], s[6:7] offset:256
	s_add_u32 s6, s16, 0x50000
	s_addc_u32 s7, s17, 0
	s_waitcnt vmcnt(15)
	v_lshlrev_b32_e32 v151, 16, v202
	v_and_b32_e32 v202, 0xffff0000, v202
	v_add_f32_e32 v28, v28, v151
	v_add_f32_e32 v29, v29, v202
	v_lshlrev_b32_e32 v151, 16, v203
	v_and_b32_e32 v203, 0xffff0000, v203
	v_add_f32_e32 v30, v30, v151
	v_add_f32_e32 v31, v31, v203
	v_lshlrev_b32_e32 v151, 16, v204
	v_and_b32_e32 v204, 0xffff0000, v204
	v_add_f32_e32 v24, v24, v151
	v_add_f32_e32 v25, v25, v204
	v_lshlrev_b32_e32 v151, 16, v205
	v_and_b32_e32 v205, 0xffff0000, v205
	v_add_f32_e32 v26, v26, v151
	v_add_f32_e32 v27, v27, v205
	v_cvt_pk_bf16_f32 v202, v28, v29
	v_cvt_pk_bf16_f32 v203, v30, v31
	v_cvt_pk_bf16_f32 v204, v24, v25
	v_cvt_pk_bf16_f32 v205, v26, v27
	global_store_dwordx4 v150, v[202:205], s[6:7]
	s_waitcnt vmcnt(15)
	v_lshlrev_b32_e32 v151, 16, v210
	v_and_b32_e32 v210, 0xffff0000, v210
	v_add_f32_e32 v20, v20, v151
	v_add_f32_e32 v21, v21, v210
	v_lshlrev_b32_e32 v151, 16, v211
	v_and_b32_e32 v211, 0xffff0000, v211
	v_add_f32_e32 v22, v22, v151
	v_add_f32_e32 v23, v23, v211
	v_lshlrev_b32_e32 v151, 16, v212
	v_and_b32_e32 v212, 0xffff0000, v212
	v_add_f32_e32 v16, v16, v151
	v_add_f32_e32 v17, v17, v212
	v_lshlrev_b32_e32 v151, 16, v213
	v_and_b32_e32 v213, 0xffff0000, v213
	v_add_f32_e32 v18, v18, v151
	v_add_f32_e32 v19, v19, v213
	v_cvt_pk_bf16_f32 v210, v20, v21
	v_cvt_pk_bf16_f32 v211, v22, v23
	v_cvt_pk_bf16_f32 v212, v16, v17
	v_cvt_pk_bf16_f32 v213, v18, v19
	global_store_dwordx4 v150, v[210:213], s[6:7] offset:256
	s_add_u32 s6, s16, 0x58000
	s_addc_u32 s7, s17, 0
	s_waitcnt vmcnt(15)
	v_lshlrev_b32_e32 v151, 16, v214
	v_and_b32_e32 v214, 0xffff0000, v214
	v_add_f32_e32 v12, v12, v151
	v_add_f32_e32 v13, v13, v214
	v_lshlrev_b32_e32 v151, 16, v215
	v_and_b32_e32 v215, 0xffff0000, v215
	v_add_f32_e32 v14, v14, v151
	v_add_f32_e32 v15, v15, v215
	v_lshlrev_b32_e32 v151, 16, v216
	v_and_b32_e32 v216, 0xffff0000, v216
	v_add_f32_e32 v8, v8, v151
	v_add_f32_e32 v9, v9, v216
	v_lshlrev_b32_e32 v151, 16, v217
	v_and_b32_e32 v217, 0xffff0000, v217
	v_add_f32_e32 v10, v10, v151
	v_add_f32_e32 v11, v11, v217
	v_cvt_pk_bf16_f32 v214, v12, v13
	v_cvt_pk_bf16_f32 v215, v14, v15
	v_cvt_pk_bf16_f32 v216, v8, v9
	v_cvt_pk_bf16_f32 v217, v10, v11
	global_store_dwordx4 v150, v[214:217], s[6:7]
	s_waitcnt vmcnt(15)
	v_lshlrev_b32_e32 v151, 16, v218
	v_and_b32_e32 v218, 0xffff0000, v218
	v_add_f32_e32 v4, v4, v151
	v_add_f32_e32 v5, v5, v218
	v_lshlrev_b32_e32 v151, 16, v219
	v_and_b32_e32 v219, 0xffff0000, v219
	v_add_f32_e32 v6, v6, v151
	v_add_f32_e32 v7, v7, v219
	v_lshlrev_b32_e32 v151, 16, v220
	v_and_b32_e32 v220, 0xffff0000, v220
	v_add_f32_e32 v0, v0, v151
	v_add_f32_e32 v1, v1, v220
	v_lshlrev_b32_e32 v151, 16, v221
	v_and_b32_e32 v221, 0xffff0000, v221
	v_add_f32_e32 v2, v2, v151
	v_add_f32_e32 v3, v3, v221
	v_cvt_pk_bf16_f32 v218, v4, v5
	v_cvt_pk_bf16_f32 v219, v6, v7
	v_cvt_pk_bf16_f32 v220, v0, v1
	v_cvt_pk_bf16_f32 v221, v2, v3
	global_store_dwordx4 v150, v[218:221], s[6:7] offset:256
	s_branch .Lp7_done

; #define PG8_BAR __builtin_amdgcn_s_barrier()
; template <class Epi, class Sched, bool ALIGN_EPI = false, bool SP2 = false>
; __device__ __forceinline__ void gemm_phase(PG8_LAS unsigned char* lds, const Gemm g, const Sched& S, const Epi& E) {
;     ...
;         if constexpr (ALIGN_EPI) { if (wr == 0) PG8_BAR; }
;         if constexpr (!Epi::AFTER_DRAIN) { E(acc, cur, wr, wc, fr, fq); S.done(cur); }
;         if (!has_next) break;
; #pragma unroll
;         for (int a = 0; a < 2; ++a)
; #pragma unroll
;             for (int b = 0; b < 2; ++b)
; #pragma unroll
;                 for (int m = 0; m < 4; ++m)
; #pragma unroll
;                     for (int n = 0; n < 2; ++n) acc[a][b][m][n] = zero4_;
;         cur = nxt; cA = nA; cB = nB; ++ui;
;         if constexpr (ALIGN_EPI) { if (wr == 1) PG8_BAR; }
;     }
.Lp7_done:
	s_and_b64 vcc, exec, s[0:1]
	s_mov_b64 s[0:1], -1
	s_cbranch_vccnz .LBB0_1184
	s_andn2_b64 vcc, exec, s[2:3]
	s_cbranch_vccnz .LBB0_1183
	s_barrier
	s_branch .LBB0_1183
